# half-peel (first two sub-phases of each GEMM tile peeled, jump into loop middle) + 64-byte aligned steady loop heads
# baseline (speedup 1.0000x reference)
; #define PG8_STAGE(bufoff, gbase, voff) do { _Pragma("unroll") for (int _i = 0; _i < 2; ++_i) \
;         __builtin_amdgcn_global_load_lds((const unsigned*)((const char*)(gbase) + (voff)[_i]), (PG8_LAS unsigned*)(lds + (bufoff) + ldsw + _i * 8192), 16, 0, 0); } while (0)
; #define PG8_LDA(dst, b, h) do { _Pragma("unroll") for (int m = 0; m < 4; ++m) _Pragma("unroll") for (int k = 0; k < 2; ++k) dst[m][k] = *(const PG8_LAS bf16x8*)(lds + PG8_SA(b, h) + aoff + m * 2048 + k * 1024); } while (0)
; #define PG8_WAIT_V(n) asm volatile("s_waitcnt vmcnt(" #n ")" ::: "memory")
; #define PG8_BAR __builtin_amdgcn_s_barrier()
; template <class Epi, class Sched, bool ALIGN_EPI = false>
; __device__ __forceinline__ void gemm_phase8(PG8_LAS unsigned char* lds, const Gemm g, const Sched& S, const Epi& E) {
;     ...
;         const bool has_next = S.next(ui + 1, nxt);
;         const size_t nko = (has_next && nxt.kp > 0) ? (size_t)nxt.kp * g.kpiece : 0;
;         const char* nA = has_next ? (const char*)g.A + (size_t)nxt.pm * tstepA + (size_t)nxt.pn * astep + nko : cA; const char* nB = has_next ? (const char*)g.Bt + (size_t)nxt.pn * tstepB + nko : cB;
;         const int nt = (cur.kp < 0 ? g.K : g.kpiece) / 128;
;         for (int t = 0; t < nt; t += 2) {
;             const bool last = (t == nt - 2);
;             const char* a1 = cA + (size_t)(t + 1) * kstep;
;             const char* a2 = last ? nA : cA + (size_t)(t + 2) * kstep; const char* b2 = last ? nB : cB + (size_t)(t + 2) * kstep;
;             const char* a3 = a2 + kstep; const char* b3 = b2 + kstep;
;             if (last && has_next) S.a_ready(nxt);
;             PG8_LDB(B0, 0, 0); PG8_LDB(B1, 0, 1); PG8_SCHED; PG8_LDA(At, 0, 0); PG8_STAGE(PG8_SA(1, 1), a1 + hstepA, voffA);
;             PG8_WAIT_V(8); PG8_WAIT_L(0); PG8_BAR; PG8_MMA(0, 0, At, B0); PG8_MMA(0, 1, At, B1); PG8_BAR; PG8_SCHED;
;             PG8_LDA(At, 0, 1); PG8_STAGE(PG8_SB(0, 0), b2, voffB); PG8_STAGE(PG8_SB(0, 1), b2 + hstepB, voffB); PG8_STAGE(PG8_SA(0, 0), a2, voffA);
;             PG8_WAIT_V(8); PG8_WAIT_L(0); PG8_BAR; PG8_MMA(1, 0, At, B0); PG8_MMA(1, 1, At, B1); PG8_BAR; PG8_SCHED;
;             PG8_LDB(B0, 1, 0); PG8_LDB(B1, 1, 1); PG8_SCHED; PG8_LDA(At, 1, 0); PG8_STAGE(PG8_SA(0, 1), a2 + hstepA, voffA);
;             PG8_WAIT_V(8); PG8_WAIT_L(0); PG8_BAR; PG8_MMA(0, 0, At, B0); PG8_MMA(0, 1, At, B1); PG8_BAR; PG8_SCHED;
.LBB0_324:
	s_ashr_i32 s15, s14, 31
	s_lshl_b64 s[16:17], s[14:15], 19
	s_add_u32 s16, s28, s16
	s_addc_u32 s17, s29, s17
	s_and_b64 s[18:19], s[2:3], exec
	s_cselect_b32 s15, s17, s23
	s_cselect_b32 s61, s16, s22
	s_ashr_i32 s13, s12, 31
	s_lshl_b64 s[18:19], s[12:13], 19
	s_add_u32 s18, s4, s18
	s_addc_u32 s19, s5, s19
	s_and_b64 s[26:27], s[2:3], exec
	s_cselect_b32 s13, s19, s25
	s_cselect_b32 s62, s18, s24
	s_add_u32 s22, s22, 0x40080
	s_addc_u32 s23, s23, 0
	s_add_u32 s63, s24, 0x100
	s_addc_u32 s64, s25, 0
	s_mov_b32 s65, -2
	ds_read_b128 v[18:21], v191
	ds_read_b128 v[26:29], v191 offset:2048
	ds_read_b128 v[22:25], v192
	ds_read_b128 v[30:33], v192 offset:2048
	ds_read_b128 v[2:5], v193
	ds_read_b128 v[10:13], v193 offset:2048
	ds_read_b128 v[6:9], v194
	ds_read_b128 v[14:17], v194 offset:2048
	s_add_u32 s24, s22, 0xfffc0080
	s_addc_u32 s25, s23, -1
	s_cmp_eq_u32 s65, 12
	s_cselect_b32 s27, s15, s25
	s_cselect_b32 s26, s61, s24
	s_cselect_b32 s25, s13, s64
	s_cselect_b32 s24, s62, s63
	s_add_i32 m0, s21, 0xc000
	ds_read_b128 v[178:181], v195
	ds_read_b128 v[198:201], v195 offset:2048
	ds_read_b128 v[182:185], v196
	ds_read_b128 v[202:205], v196 offset:2048
	ds_read_b128 v[206:209], v195 offset:4096
	ds_read_b128 v[214:217], v195 offset:6144
	ds_read_b128 v[210:213], v196 offset:4096
	ds_read_b128 v[218:221], v196 offset:6144
	global_load_lds_dwordx4 v170, s[22:23]
	s_add_i32 m0, s21, 0xe000
	s_nop 0
	global_load_lds_dwordx4 v172, s[22:23]
	s_waitcnt vmcnt(8)
	s_waitcnt lgkmcnt(0)
	s_barrier
	s_setprio 1
	s_waitcnt lgkmcnt(0)
	v_mfma_scale_f32_16x16x128_f8f6f4 v[158:161], v[18:25], v[178:185], 0, v1, v186 op_sel_hi:[0,0,0]
	v_mfma_scale_f32_16x16x128_f8f6f4 v[150:153], v[26:33], v[178:185], 0, v1, v186 op_sel_hi:[0,0,0]
	v_mfma_scale_f32_16x16x128_f8f6f4 v[142:145], v[18:25], v[198:205], 0, v1, v186 op_sel_hi:[0,0,0]
	v_mfma_scale_f32_16x16x128_f8f6f4 v[134:137], v[26:33], v[198:205], 0, v1, v186 op_sel_hi:[0,0,0]
	v_mfma_scale_f32_16x16x128_f8f6f4 v[126:129], v[18:25], v[206:213], 0, v1, v186 op_sel_hi:[0,0,0]
	v_mfma_scale_f32_16x16x128_f8f6f4 v[118:121], v[26:33], v[206:213], 0, v1, v186 op_sel_hi:[0,0,0]
	v_mfma_scale_f32_16x16x128_f8f6f4 v[110:113], v[18:25], v[214:221], 0, v1, v186 op_sel_hi:[0,0,0]
	v_mfma_scale_f32_16x16x128_f8f6f4 v[102:105], v[26:33], v[214:221], 0, v1, v186 op_sel_hi:[0,0,0]
	s_setprio 0
	s_setprio 1
	v_mfma_scale_f32_16x16x128_f8f6f4 v[154:157], v[2:9], v[178:185], 0, v1, v186 op_sel_hi:[0,0,0]
	v_mfma_scale_f32_16x16x128_f8f6f4 v[146:149], v[10:17], v[178:185], 0, v1, v186 op_sel_hi:[0,0,0]
	v_mfma_scale_f32_16x16x128_f8f6f4 v[138:141], v[2:9], v[198:205], 0, v1, v186 op_sel_hi:[0,0,0]
	v_mfma_scale_f32_16x16x128_f8f6f4 v[130:133], v[10:17], v[198:205], 0, v1, v186 op_sel_hi:[0,0,0]
	v_mfma_scale_f32_16x16x128_f8f6f4 v[122:125], v[2:9], v[206:213], 0, v1, v186 op_sel_hi:[0,0,0]
	v_mfma_scale_f32_16x16x128_f8f6f4 v[114:117], v[10:17], v[206:213], 0, v1, v186 op_sel_hi:[0,0,0]
	v_mfma_scale_f32_16x16x128_f8f6f4 v[106:109], v[2:9], v[214:221], 0, v1, v186 op_sel_hi:[0,0,0]
	v_mfma_scale_f32_16x16x128_f8f6f4 v[98:101], v[10:17], v[214:221], 0, v1, v186 op_sel_hi:[0,0,0]
	s_setprio 0
	s_barrier
	s_add_i32 s66, s57, s30
	s_mov_b32 m0, s66
	ds_read_b128 v[198:201], v195 offset:16384
	ds_read_b128 v[206:209], v195 offset:18432
	ds_read_b128 v[202:205], v196 offset:16384
	ds_read_b128 v[210:213], v196 offset:18432
	ds_read_b128 v[214:217], v195 offset:20480
	ds_read_b128 v[222:225], v195 offset:22528
	ds_read_b128 v[218:221], v196 offset:20480
	ds_read_b128 v[226:229], v196 offset:22528
	global_load_lds_dwordx4 v164, s[24:25]
	s_add_i32 m0, s66, 0x2000
	s_add_u32 s66, s24, 0x40000
	s_addc_u32 s67, s25, 0
	s_add_i32 s72, s58, s30
	global_load_lds_dwordx4 v168, s[24:25]
	s_mov_b32 m0, s72
	s_nop 0
	global_load_lds_dwordx4 v164, s[66:67]
	s_add_i32 m0, s72, 0x2000
	s_nop 0
	global_load_lds_dwordx4 v168, s[66:67]
	s_mov_b32 m0, s21
	s_nop 0
	global_load_lds_dwordx4 v162, s[26:27]
	s_mov_b32 m0, s34
	s_nop 0
	global_load_lds_dwordx4 v166, s[26:27]
	s_waitcnt vmcnt(8)
	s_waitcnt lgkmcnt(0)
	s_barrier
	s_setprio 1
	s_waitcnt lgkmcnt(0)
	v_mfma_scale_f32_16x16x128_f8f6f4 v[94:97], v[18:25], v[198:205], 0, v1, v186 op_sel_hi:[0,0,0]
	v_mfma_scale_f32_16x16x128_f8f6f4 v[86:89], v[26:33], v[198:205], 0, v1, v186 op_sel_hi:[0,0,0]
	v_mfma_scale_f32_16x16x128_f8f6f4 v[78:81], v[18:25], v[206:213], 0, v1, v186 op_sel_hi:[0,0,0]
	v_mfma_scale_f32_16x16x128_f8f6f4 v[70:73], v[26:33], v[206:213], 0, v1, v186 op_sel_hi:[0,0,0]
	v_mfma_scale_f32_16x16x128_f8f6f4 v[62:65], v[18:25], v[214:221], 0, v1, v186 op_sel_hi:[0,0,0]
	v_mfma_scale_f32_16x16x128_f8f6f4 v[54:57], v[26:33], v[214:221], 0, v1, v186 op_sel_hi:[0,0,0]
	v_mfma_scale_f32_16x16x128_f8f6f4 v[46:49], v[18:25], v[222:229], 0, v1, v186 op_sel_hi:[0,0,0]
	v_mfma_scale_f32_16x16x128_f8f6f4 v[38:41], v[26:33], v[222:229], 0, v1, v186 op_sel_hi:[0,0,0]
	s_setprio 0
	s_setprio 1
	v_mfma_scale_f32_16x16x128_f8f6f4 v[90:93], v[2:9], v[198:205], 0, v1, v186 op_sel_hi:[0,0,0]
	v_mfma_scale_f32_16x16x128_f8f6f4 v[82:85], v[10:17], v[198:205], 0, v1, v186 op_sel_hi:[0,0,0]
	v_mfma_scale_f32_16x16x128_f8f6f4 v[74:77], v[2:9], v[206:213], 0, v1, v186 op_sel_hi:[0,0,0]
	v_mfma_scale_f32_16x16x128_f8f6f4 v[66:69], v[10:17], v[206:213], 0, v1, v186 op_sel_hi:[0,0,0]
	v_mfma_scale_f32_16x16x128_f8f6f4 v[58:61], v[2:9], v[214:221], 0, v1, v186 op_sel_hi:[0,0,0]
	v_mfma_scale_f32_16x16x128_f8f6f4 v[50:53], v[10:17], v[214:221], 0, v1, v186 op_sel_hi:[0,0,0]
	v_mfma_scale_f32_16x16x128_f8f6f4 v[42:45], v[2:9], v[222:229], 0, v1, v186 op_sel_hi:[0,0,0]
	v_mfma_scale_f32_16x16x128_f8f6f4 v[34:37], v[10:17], v[222:229], 0, v1, v186 op_sel_hi:[0,0,0]
	s_setprio 0
	s_barrier
	s_branch .Lmid_0
	.p2align	6

; #define PG8_STAGE(bufoff, gbase, voff) do { _Pragma("unroll") for (int _i = 0; _i < 2; ++_i) \
;         __builtin_amdgcn_global_load_lds((const unsigned*)((const char*)(gbase) + (voff)[_i]), (PG8_LAS unsigned*)(lds + (bufoff) + ldsw + _i * 8192), 16, 0, 0); } while (0)
; #define PG8_LDA(dst, b, h) do { _Pragma("unroll") for (int m = 0; m < 4; ++m) _Pragma("unroll") for (int k = 0; k < 2; ++k) dst[m][k] = *(const PG8_LAS bf16x8*)(lds + PG8_SA(b, h) + aoff + m * 2048 + k * 1024); } while (0)
; #define PG8_LDB(dst, b, h) do { _Pragma("unroll") for (int n = 0; n < 2; ++n) _Pragma("unroll") for (int k = 0; k < 2; ++k) dst[n][k] = *(const PG8_LAS bf16x8*)(lds + PG8_SB(b, h) + boff + n * 2048 + k * 1024); } while (0)
; #define PG8_MMA(ai, bj, At, Bt) do { __builtin_amdgcn_s_setprio(1); _Pragma("unroll") for (int m = 0; m < 4; ++m) _Pragma("unroll") for (int n = 0; n < 2; ++n) _Pragma("unroll") for (int k = 0; k < 2; ++k) \
;         acc[ai][bj][m][n] = __builtin_amdgcn_mfma_f32_16x16x32_bf16(Bt[n][k], At[m][k], acc[ai][bj][m][n], 0, 0, 0); __builtin_amdgcn_s_setprio(0); } while (0)
; #define PG8_WAIT_V(n) asm volatile("s_waitcnt vmcnt(" #n ")" ::: "memory")
; #define PG8_BAR __builtin_amdgcn_s_barrier()
; template <class Epi, class Sched, bool ALIGN_EPI = false>
; __device__ __forceinline__ void gemm_phase8(PG8_LAS unsigned char* lds, const Gemm g, const Sched& S, const Epi& E) {
;     ...
;         const int nt = (cur.kp < 0 ? g.K : g.kpiece) / 128;
;         for (int t = 0; t < nt; t += 2) {
;             const bool last = (t == nt - 2);
;             const char* a1 = cA + (size_t)(t + 1) * kstep;
;             const char* a2 = last ? nA : cA + (size_t)(t + 2) * kstep; const char* b2 = last ? nB : cB + (size_t)(t + 2) * kstep;
;             const char* a3 = a2 + kstep; const char* b3 = b2 + kstep;
;             if (last && has_next) S.a_ready(nxt);
;             PG8_LDB(B0, 0, 0); PG8_LDB(B1, 0, 1); PG8_SCHED; PG8_LDA(At, 0, 0); PG8_STAGE(PG8_SA(1, 1), a1 + hstepA, voffA);
;             PG8_WAIT_V(8); PG8_WAIT_L(0); PG8_BAR; PG8_MMA(0, 0, At, B0); PG8_MMA(0, 1, At, B1); PG8_BAR; PG8_SCHED;
;             PG8_LDA(At, 0, 1); PG8_STAGE(PG8_SB(0, 0), b2, voffB); PG8_STAGE(PG8_SB(0, 1), b2 + hstepB, voffB); PG8_STAGE(PG8_SA(0, 0), a2, voffA);
;             PG8_WAIT_V(8); PG8_WAIT_L(0); PG8_BAR; PG8_MMA(1, 0, At, B0); PG8_MMA(1, 1, At, B1); PG8_BAR; PG8_SCHED;
.LBB0_501:
	s_cmp_gt_i32 s24, -1
	s_cselect_b64 s[26:27], -1, 0
	s_cmp_lt_i32 s24, 0
	s_cselect_b32 s25, 44, 4
	s_add_i32 s81, s25, -2
	s_add_u32 s28, s28, 0xb0080
	s_addc_u32 s29, s29, 0
	s_add_u32 s82, s30, 0x100
	s_mov_b32 s34, 0
	s_addc_u32 s83, s31, 0
	ds_read_b128 v[18:21], v187
	ds_read_b128 v[26:29], v187 offset:2048
	ds_read_b128 v[22:25], v188
	ds_read_b128 v[30:33], v188 offset:2048
	ds_read_b128 v[2:5], v189
	ds_read_b128 v[10:13], v189 offset:2048
	ds_read_b128 v[6:9], v190
	ds_read_b128 v[14:17], v190 offset:2048
	s_add_i32 s84, s34, 2
	s_add_u32 s30, s28, 0xfff50080
	s_addc_u32 s31, s29, -1
	s_cmp_eq_u32 s81, s34
	s_cselect_b32 s34, s20, s30
	s_cselect_b32 s35, s21, s31
	s_cselect_b32 s31, s23, s83
	s_cselect_b32 s30, s22, s82
	s_add_i32 m0, s54, 0xc000
	ds_read_b128 v[174:177], v191
	ds_read_b128 v[194:197], v191 offset:2048
	ds_read_b128 v[178:181], v192
	ds_read_b128 v[198:201], v192 offset:2048
	ds_read_b128 v[202:205], v191 offset:4096
	ds_read_b128 v[210:213], v191 offset:6144
	ds_read_b128 v[206:209], v192 offset:4096
	ds_read_b128 v[214:217], v192 offset:6144
	global_load_lds_dwordx4 v170, s[28:29]
	s_add_i32 m0, s54, 0xe000
	s_nop 0
	global_load_lds_dwordx4 v172, s[28:29]
	s_waitcnt vmcnt(8)
	s_waitcnt lgkmcnt(0)
	s_barrier
	s_setprio 1
	s_waitcnt lgkmcnt(0)
	v_mfma_scale_f32_16x16x128_f8f6f4 v[158:161], v[18:25], v[174:181], 0, v1, v182 op_sel_hi:[0,0,0]
	v_mfma_scale_f32_16x16x128_f8f6f4 v[154:157], v[26:33], v[174:181], 0, v1, v182 op_sel_hi:[0,0,0]
	v_mfma_scale_f32_16x16x128_f8f6f4 v[142:145], v[18:25], v[194:201], 0, v1, v182 op_sel_hi:[0,0,0]
	v_mfma_scale_f32_16x16x128_f8f6f4 v[138:141], v[26:33], v[194:201], 0, v1, v182 op_sel_hi:[0,0,0]
	v_mfma_scale_f32_16x16x128_f8f6f4 v[126:129], v[18:25], v[202:209], 0, v1, v182 op_sel_hi:[0,0,0]
	v_mfma_scale_f32_16x16x128_f8f6f4 v[122:125], v[26:33], v[202:209], 0, v1, v182 op_sel_hi:[0,0,0]
	v_mfma_scale_f32_16x16x128_f8f6f4 v[110:113], v[18:25], v[210:217], 0, v1, v182 op_sel_hi:[0,0,0]
	v_mfma_scale_f32_16x16x128_f8f6f4 v[106:109], v[26:33], v[210:217], 0, v1, v182 op_sel_hi:[0,0,0]
	s_setprio 0
	s_setprio 1
	v_mfma_scale_f32_16x16x128_f8f6f4 v[150:153], v[2:9], v[174:181], 0, v1, v182 op_sel_hi:[0,0,0]
	v_mfma_scale_f32_16x16x128_f8f6f4 v[146:149], v[10:17], v[174:181], 0, v1, v182 op_sel_hi:[0,0,0]
	v_mfma_scale_f32_16x16x128_f8f6f4 v[134:137], v[2:9], v[194:201], 0, v1, v182 op_sel_hi:[0,0,0]
	v_mfma_scale_f32_16x16x128_f8f6f4 v[130:133], v[10:17], v[194:201], 0, v1, v182 op_sel_hi:[0,0,0]
	v_mfma_scale_f32_16x16x128_f8f6f4 v[118:121], v[2:9], v[202:209], 0, v1, v182 op_sel_hi:[0,0,0]
	v_mfma_scale_f32_16x16x128_f8f6f4 v[114:117], v[10:17], v[202:209], 0, v1, v182 op_sel_hi:[0,0,0]
	v_mfma_scale_f32_16x16x128_f8f6f4 v[102:105], v[2:9], v[210:217], 0, v1, v182 op_sel_hi:[0,0,0]
	v_mfma_scale_f32_16x16x128_f8f6f4 v[98:101], v[10:17], v[210:217], 0, v1, v182 op_sel_hi:[0,0,0]
	s_setprio 0
	s_barrier
	s_add_i32 s85, s65, s53
	s_mov_b32 m0, s85
	ds_read_b128 v[194:197], v191 offset:16384
	ds_read_b128 v[202:205], v191 offset:18432
	ds_read_b128 v[198:201], v192 offset:16384
	ds_read_b128 v[206:209], v192 offset:18432
	ds_read_b128 v[210:213], v191 offset:20480
	ds_read_b128 v[218:221], v191 offset:22528
	ds_read_b128 v[214:217], v192 offset:20480
	ds_read_b128 v[222:225], v192 offset:22528
	global_load_lds_dwordx4 v164, s[30:31]
	s_add_i32 m0, s85, 0x2000
	s_add_u32 s88, s30, 0xb0000
	s_addc_u32 s89, s31, 0
	s_add_i32 s85, s66, s53
	global_load_lds_dwordx4 v168, s[30:31]
	s_mov_b32 m0, s85
	s_nop 0
	global_load_lds_dwordx4 v164, s[88:89]
	s_add_i32 m0, s85, 0x2000
	s_nop 0
	global_load_lds_dwordx4 v168, s[88:89]
	s_mov_b32 m0, s54
	s_nop 0
	global_load_lds_dwordx4 v162, s[34:35]
	s_mov_b32 m0, s55
	s_nop 0
	global_load_lds_dwordx4 v166, s[34:35]
	s_waitcnt vmcnt(8)
	s_waitcnt lgkmcnt(0)
	s_barrier
	s_setprio 1
	s_waitcnt lgkmcnt(0)
	v_mfma_scale_f32_16x16x128_f8f6f4 v[94:97], v[18:25], v[194:201], 0, v1, v182 op_sel_hi:[0,0,0]
	v_mfma_scale_f32_16x16x128_f8f6f4 v[90:93], v[26:33], v[194:201], 0, v1, v182 op_sel_hi:[0,0,0]
	v_mfma_scale_f32_16x16x128_f8f6f4 v[78:81], v[18:25], v[202:209], 0, v1, v182 op_sel_hi:[0,0,0]
	v_mfma_scale_f32_16x16x128_f8f6f4 v[74:77], v[26:33], v[202:209], 0, v1, v182 op_sel_hi:[0,0,0]
	v_mfma_scale_f32_16x16x128_f8f6f4 v[62:65], v[18:25], v[210:217], 0, v1, v182 op_sel_hi:[0,0,0]
	v_mfma_scale_f32_16x16x128_f8f6f4 v[58:61], v[26:33], v[210:217], 0, v1, v182 op_sel_hi:[0,0,0]
	v_mfma_scale_f32_16x16x128_f8f6f4 v[46:49], v[18:25], v[218:225], 0, v1, v182 op_sel_hi:[0,0,0]
	v_mfma_scale_f32_16x16x128_f8f6f4 v[42:45], v[26:33], v[218:225], 0, v1, v182 op_sel_hi:[0,0,0]
	s_setprio 0
	s_setprio 1
	v_mfma_scale_f32_16x16x128_f8f6f4 v[86:89], v[2:9], v[194:201], 0, v1, v182 op_sel_hi:[0,0,0]
	v_mfma_scale_f32_16x16x128_f8f6f4 v[82:85], v[10:17], v[194:201], 0, v1, v182 op_sel_hi:[0,0,0]
	v_mfma_scale_f32_16x16x128_f8f6f4 v[70:73], v[2:9], v[202:209], 0, v1, v182 op_sel_hi:[0,0,0]
	v_mfma_scale_f32_16x16x128_f8f6f4 v[66:69], v[10:17], v[202:209], 0, v1, v182 op_sel_hi:[0,0,0]
	v_mfma_scale_f32_16x16x128_f8f6f4 v[54:57], v[2:9], v[210:217], 0, v1, v182 op_sel_hi:[0,0,0]
	v_mfma_scale_f32_16x16x128_f8f6f4 v[50:53], v[10:17], v[210:217], 0, v1, v182 op_sel_hi:[0,0,0]
	v_mfma_scale_f32_16x16x128_f8f6f4 v[38:41], v[2:9], v[218:225], 0, v1, v182 op_sel_hi:[0,0,0]
	v_mfma_scale_f32_16x16x128_f8f6f4 v[34:37], v[10:17], v[218:225], 0, v1, v182 op_sel_hi:[0,0,0]
	s_setprio 0
	s_barrier
	s_branch .Lmid_1
	.p2align	6

; #define PG8_STAGE(bufoff, gbase, voff) do { _Pragma("unroll") for (int _i = 0; _i < 2; ++_i) \
;         __builtin_amdgcn_global_load_lds((const unsigned*)((const char*)(gbase) + (voff)[_i]), (PG8_LAS unsigned*)(lds + (bufoff) + ldsw + _i * 8192), 16, 0, 0); } while (0)
; #define PG8_LDA(dst, b, h) do { _Pragma("unroll") for (int m = 0; m < 4; ++m) _Pragma("unroll") for (int k = 0; k < 2; ++k) dst[m][k] = *(const PG8_LAS bf16x8*)(lds + PG8_SA(b, h) + aoff + m * 2048 + k * 1024); } while (0)
; #define PG8_LDB(dst, b, h) do { _Pragma("unroll") for (int n = 0; n < 2; ++n) _Pragma("unroll") for (int k = 0; k < 2; ++k) dst[n][k] = *(const PG8_LAS bf16x8*)(lds + PG8_SB(b, h) + boff + n * 2048 + k * 1024); } while (0)
; #define PG8_WAIT_V(n) asm volatile("s_waitcnt vmcnt(" #n ")" ::: "memory")
; #define PG8_BAR __builtin_amdgcn_s_barrier()
; template <class Epi, class Sched, bool ALIGN_EPI = false>
; __device__ __forceinline__ void gemm_phase(PG8_LAS unsigned char* lds, const Gemm g, const Sched& S, const Epi& E) {
;     ...
;     for (;;) {
;         const bool has_next = S.next(ui + 1, nxt);
;         const size_t nko = (has_next && nxt.kp > 0) ? (size_t)nxt.kp * g.kpiece * 2 : 0;
;         const char* nA = has_next ? (const char*)g.A + (size_t)nxt.pm * tstepA + (size_t)nxt.pn * astep + nko : cA; const char* nB = has_next ? (const char*)g.Bt + (size_t)nxt.pn * tstepB + nko : cB;
;         const int nt = (cur.kp < 0 ? g.K : g.kpiece) / BK;
;         for (int t = 0; t < nt; t += 2) {
;             const bool last = (t == nt - 2);
;             const char* a1 = cA + (size_t)(t + 1) * kstep;
;             const char* a2 = last ? nA : cA + (size_t)(t + 2) * kstep; const char* b2 = last ? nB : cB + (size_t)(t + 2) * kstep;
;             const char* a3 = a2 + kstep; const char* b3 = b2 + kstep;
;             if (last && has_next) S.a_ready(nxt);
;             PG8_LDB(B0, 0, 0); PG8_LDB(B1, 0, 1); PG8_SCHED; PG8_LDA(At, 0, 0); PG8_STAGE(PG8_SA(1, 1), a1 + hstepA, voffA);
;             PG8_WAIT_V(8); PG8_WAIT_L(0); PG8_BAR; PG8_MMA(0, 0, At, B0); PG8_MMA(0, 1, At, B1); PG8_BAR; PG8_SCHED;
;             PG8_LDA(At, 0, 1); PG8_STAGE(PG8_SB(0, 0), b2, voffB); PG8_STAGE(PG8_SB(0, 1), b2 + hstepB, voffB); PG8_STAGE(PG8_SA(0, 0), a2, voffA);
;             PG8_WAIT_V(8); PG8_WAIT_L(0); PG8_BAR; PG8_MMA(1, 0, At, B0); PG8_MMA(1, 1, At, B1); PG8_BAR; PG8_SCHED;
.LBB0_733:
	s_ashr_i32 s27, s26, 31
	s_lshl_b64 s[28:29], s[26:27], 20
	s_add_u32 s28, s56, s28
	s_addc_u32 s29, s57, s29
	s_and_b64 s[30:31], s[2:3], exec
	s_cselect_b32 s13, s29, s53
	s_cselect_b32 s27, s28, s52
	s_ashr_i32 s25, s24, 31
	s_lshl_b64 s[30:31], s[24:25], 20
	s_add_u32 s30, s4, s30
	s_addc_u32 s31, s5, s31
	s_and_b64 s[54:55], s[2:3], exec
	s_cselect_b32 s25, s31, s35
	s_cselect_b32 s82, s30, s34
	s_add_u32 s52, s52, 0x80080
	s_addc_u32 s53, s53, 0
	s_add_u32 s83, s34, 0x100
	s_addc_u32 s84, s35, 0
	s_mov_b32 s85, -2
	ds_read_b128 v[130:133], v165
	ds_read_b128 v[134:137], v165 offset:1024
	ds_read_b128 v[158:161], v165 offset:2048
	ds_read_b128 v[170:173], v165 offset:3072
	ds_read_b128 v[174:177], v166
	ds_read_b128 v[178:181], v166 offset:1024
	ds_read_b128 v[182:185], v166 offset:2048
	ds_read_b128 v[186:189], v166 offset:3072
	s_add_u32 s34, s52, 0xfff80080
	s_addc_u32 s35, s53, -1
	s_cmp_eq_u32 s85, 28
	s_cselect_b32 s55, s13, s35
	s_cselect_b32 s54, s27, s34
	s_cselect_b32 s35, s25, s84
	s_cselect_b32 s34, s82, s83
	s_add_i32 m0, s61, 0xc000
	ds_read_b128 v[190:193], v167
	ds_read_b128 v[194:197], v167 offset:1024
	ds_read_b128 v[198:201], v167 offset:2048
	ds_read_b128 v[202:205], v167 offset:3072
	ds_read_b128 v[206:209], v167 offset:4096
	ds_read_b128 v[210:213], v167 offset:5120
	ds_read_b128 v[214:217], v167 offset:6144
	ds_read_b128 v[218:221], v167 offset:7168
	global_load_lds_dwordx4 v150, s[52:53]
	s_add_i32 m0, s61, 0xe000
	s_nop 0
	global_load_lds_dwordx4 v152, s[52:53]
	s_waitcnt vmcnt(8)
	s_waitcnt lgkmcnt(0)
	s_barrier
	s_waitcnt lgkmcnt(0)
	v_mfma_f32_16x16x32_bf16 v[126:129], v[130:133], v[190:193], 0
	v_mfma_f32_16x16x32_bf16 v[122:125], v[158:161], v[190:193], 0
	v_mfma_f32_16x16x32_bf16 v[114:117], v[130:133], v[198:201], 0
	v_mfma_f32_16x16x32_bf16 v[106:109], v[158:161], v[198:201], 0
	v_mfma_f32_16x16x32_bf16 v[98:101], v[130:133], v[206:209], 0
	v_mfma_f32_16x16x32_bf16 v[90:93], v[158:161], v[206:209], 0
	v_mfma_f32_16x16x32_bf16 v[82:85], v[130:133], v[214:217], 0
	v_mfma_f32_16x16x32_bf16 v[74:77], v[158:161], v[214:217], 0
	v_mfma_f32_16x16x32_bf16 v[126:129], v[134:137], v[194:197], v[126:129]
	v_mfma_f32_16x16x32_bf16 v[122:125], v[170:173], v[194:197], v[122:125]
	v_mfma_f32_16x16x32_bf16 v[114:117], v[134:137], v[202:205], v[114:117]
	v_mfma_f32_16x16x32_bf16 v[106:109], v[170:173], v[202:205], v[106:109]
	v_mfma_f32_16x16x32_bf16 v[98:101], v[134:137], v[210:213], v[98:101]
	v_mfma_f32_16x16x32_bf16 v[90:93], v[170:173], v[210:213], v[90:93]
	v_mfma_f32_16x16x32_bf16 v[82:85], v[134:137], v[218:221], v[82:85]
	v_mfma_f32_16x16x32_bf16 v[74:77], v[170:173], v[218:221], v[74:77]
	v_mfma_f32_16x16x32_bf16 v[118:121], v[174:177], v[190:193], 0
	v_mfma_f32_16x16x32_bf16 v[110:113], v[182:185], v[190:193], 0
	v_mfma_f32_16x16x32_bf16 v[102:105], v[174:177], v[198:201], 0
	v_mfma_f32_16x16x32_bf16 v[94:97], v[182:185], v[198:201], 0
	v_mfma_f32_16x16x32_bf16 v[86:89], v[174:177], v[206:209], 0
	v_mfma_f32_16x16x32_bf16 v[78:81], v[182:185], v[206:209], 0
	v_mfma_f32_16x16x32_bf16 v[70:73], v[174:177], v[214:217], 0
	v_mfma_f32_16x16x32_bf16 v[66:69], v[182:185], v[214:217], 0
	v_mfma_f32_16x16x32_bf16 v[118:121], v[178:181], v[194:197], v[118:121]
	v_mfma_f32_16x16x32_bf16 v[110:113], v[186:189], v[194:197], v[110:113]
	v_mfma_f32_16x16x32_bf16 v[102:105], v[178:181], v[202:205], v[102:105]
	v_mfma_f32_16x16x32_bf16 v[94:97], v[186:189], v[202:205], v[94:97]
	v_mfma_f32_16x16x32_bf16 v[86:89], v[178:181], v[210:213], v[86:89]
	v_mfma_f32_16x16x32_bf16 v[78:81], v[186:189], v[210:213], v[78:81]
	v_mfma_f32_16x16x32_bf16 v[70:73], v[178:181], v[218:221], v[70:73]
	v_mfma_f32_16x16x32_bf16 v[66:69], v[186:189], v[218:221], v[66:69]
	s_barrier
	s_add_i32 s88, s72, s58
	s_mov_b32 m0, s88
	ds_read_b128 v[190:193], v167 offset:16384
	ds_read_b128 v[194:197], v167 offset:17408
	ds_read_b128 v[198:201], v167 offset:18432
	ds_read_b128 v[202:205], v167 offset:19456
	ds_read_b128 v[206:209], v167 offset:20480
	ds_read_b128 v[210:213], v167 offset:21504
	ds_read_b128 v[214:217], v167 offset:22528
	ds_read_b128 v[218:221], v167 offset:23552
	global_load_lds_dwordx4 v140, s[34:35]
	s_add_i32 m0, s88, 0x2000
	s_add_u32 s88, s34, 0x80000
	s_addc_u32 s89, s35, 0
	s_add_i32 s90, s73, s58
	global_load_lds_dwordx4 v144, s[34:35]
	s_mov_b32 m0, s90
	s_nop 0
	global_load_lds_dwordx4 v140, s[88:89]
	s_add_i32 m0, s90, 0x2000
	s_nop 0
	global_load_lds_dwordx4 v144, s[88:89]
	s_mov_b32 m0, s61
	s_nop 0
	global_load_lds_dwordx4 v138, s[54:55]
	s_mov_b32 m0, s62
	s_nop 0
	global_load_lds_dwordx4 v142, s[54:55]
	s_waitcnt vmcnt(8)
	s_waitcnt lgkmcnt(0)
	s_barrier
	s_waitcnt lgkmcnt(0)
	v_mfma_f32_16x16x32_bf16 v[62:65], v[130:133], v[190:193], 0
	v_mfma_f32_16x16x32_bf16 v[58:61], v[158:161], v[190:193], 0
	v_mfma_f32_16x16x32_bf16 v[54:57], v[130:133], v[198:201], 0
	v_mfma_f32_16x16x32_bf16 v[46:49], v[158:161], v[198:201], 0
	v_mfma_f32_16x16x32_bf16 v[38:41], v[130:133], v[206:209], 0
	v_mfma_f32_16x16x32_bf16 v[30:33], v[158:161], v[206:209], 0
	v_mfma_f32_16x16x32_bf16 v[22:25], v[130:133], v[214:217], 0
	v_mfma_f32_16x16x32_bf16 v[14:17], v[158:161], v[214:217], 0
	v_mfma_f32_16x16x32_bf16 v[62:65], v[134:137], v[194:197], v[62:65]
	v_mfma_f32_16x16x32_bf16 v[58:61], v[170:173], v[194:197], v[58:61]
	v_mfma_f32_16x16x32_bf16 v[54:57], v[134:137], v[202:205], v[54:57]
	v_mfma_f32_16x16x32_bf16 v[46:49], v[170:173], v[202:205], v[46:49]
	v_mfma_f32_16x16x32_bf16 v[38:41], v[134:137], v[210:213], v[38:41]
	v_mfma_f32_16x16x32_bf16 v[30:33], v[170:173], v[210:213], v[30:33]
	v_mfma_f32_16x16x32_bf16 v[22:25], v[134:137], v[218:221], v[22:25]
	v_mfma_f32_16x16x32_bf16 v[14:17], v[170:173], v[218:221], v[14:17]
	v_mfma_f32_16x16x32_bf16 v[50:53], v[174:177], v[190:193], 0
	v_mfma_f32_16x16x32_bf16 v[42:45], v[182:185], v[190:193], 0
	v_mfma_f32_16x16x32_bf16 v[34:37], v[174:177], v[198:201], 0
	v_mfma_f32_16x16x32_bf16 v[26:29], v[182:185], v[198:201], 0
	v_mfma_f32_16x16x32_bf16 v[18:21], v[174:177], v[206:209], 0
	v_mfma_f32_16x16x32_bf16 v[10:13], v[182:185], v[206:209], 0
	v_mfma_f32_16x16x32_bf16 v[6:9], v[174:177], v[214:217], 0
	v_mfma_f32_16x16x32_bf16 v[2:5], v[182:185], v[214:217], 0
	v_mfma_f32_16x16x32_bf16 v[50:53], v[178:181], v[194:197], v[50:53]
	v_mfma_f32_16x16x32_bf16 v[42:45], v[186:189], v[194:197], v[42:45]
	v_mfma_f32_16x16x32_bf16 v[34:37], v[178:181], v[202:205], v[34:37]
	v_mfma_f32_16x16x32_bf16 v[26:29], v[186:189], v[202:205], v[26:29]
	v_mfma_f32_16x16x32_bf16 v[18:21], v[178:181], v[210:213], v[18:21]
	v_mfma_f32_16x16x32_bf16 v[10:13], v[186:189], v[210:213], v[10:13]
	v_mfma_f32_16x16x32_bf16 v[6:9], v[178:181], v[218:221], v[6:9]
	v_mfma_f32_16x16x32_bf16 v[2:5], v[186:189], v[218:221], v[2:5]
	s_barrier
	s_branch .Lmid_2
	.p2align	6

; #define PG8_STAGE(bufoff, gbase, voff) do { _Pragma("unroll") for (int _i = 0; _i < 2; ++_i) \
;         __builtin_amdgcn_global_load_lds((const unsigned*)((const char*)(gbase) + (voff)[_i]), (PG8_LAS unsigned*)(lds + (bufoff) + ldsw + _i * 8192), 16, 0, 0); } while (0)
; #define PG8_LDA(dst, b, h) do { _Pragma("unroll") for (int m = 0; m < 4; ++m) _Pragma("unroll") for (int k = 0; k < 2; ++k) dst[m][k] = *(const PG8_LAS bf16x8*)(lds + PG8_SA(b, h) + aoff + m * 2048 + k * 1024); } while (0)
; #define PG8_LDB(dst, b, h) do { _Pragma("unroll") for (int n = 0; n < 2; ++n) _Pragma("unroll") for (int k = 0; k < 2; ++k) dst[n][k] = *(const PG8_LAS bf16x8*)(lds + PG8_SB(b, h) + boff + n * 2048 + k * 1024); } while (0)
; #define PG8_WAIT_V(n) asm volatile("s_waitcnt vmcnt(" #n ")" ::: "memory")
; #define PG8_WAIT_L(n) asm volatile("s_waitcnt lgkmcnt(" #n ")" ::: "memory")
; #define PG8_BAR __builtin_amdgcn_s_barrier()
; template <class Epi, class Sched, bool ALIGN_EPI = false>
; __device__ __forceinline__ void gemm_phase8(PG8_LAS unsigned char* lds, const Gemm g, const Sched& S, const Epi& E) {
;     ...
;         const size_t nko = (has_next && nxt.kp > 0) ? (size_t)nxt.kp * g.kpiece : 0;
;         const char* nA = has_next ? (const char*)g.A + (size_t)nxt.pm * tstepA + (size_t)nxt.pn * astep + nko : cA; const char* nB = has_next ? (const char*)g.Bt + (size_t)nxt.pn * tstepB + nko : cB;
;         const int nt = (cur.kp < 0 ? g.K : g.kpiece) / 128;
;         for (int t = 0; t < nt; t += 2) {
;             const bool last = (t == nt - 2);
;             const char* a1 = cA + (size_t)(t + 1) * kstep;
;             const char* a2 = last ? nA : cA + (size_t)(t + 2) * kstep; const char* b2 = last ? nB : cB + (size_t)(t + 2) * kstep;
;             const char* a3 = a2 + kstep; const char* b3 = b2 + kstep;
;             if (last && has_next) S.a_ready(nxt);
;             PG8_LDB(B0, 0, 0); PG8_LDB(B1, 0, 1); PG8_SCHED; PG8_LDA(At, 0, 0); PG8_STAGE(PG8_SA(1, 1), a1 + hstepA, voffA);
;             PG8_WAIT_V(8); PG8_WAIT_L(0); PG8_BAR; PG8_MMA(0, 0, At, B0); PG8_MMA(0, 1, At, B1); PG8_BAR; PG8_SCHED;
;             PG8_LDA(At, 0, 1); PG8_STAGE(PG8_SB(0, 0), b2, voffB); PG8_STAGE(PG8_SB(0, 1), b2 + hstepB, voffB); PG8_STAGE(PG8_SA(0, 0), a2, voffA);
;             PG8_WAIT_V(8); PG8_WAIT_L(0); PG8_BAR; PG8_MMA(1, 0, At, B0); PG8_MMA(1, 1, At, B1); PG8_BAR; PG8_SCHED;
.LBB0_1186:
	s_cmp_gt_i32 s0, 0
	s_cselect_b64 s[24:25], -1, 0
	s_and_b64 s[24:25], s[22:23], s[24:25]
	s_lshl_b64 s[26:27], s[0:1], 9
	s_and_b64 s[24:25], s[24:25], exec
	s_cselect_b32 s54, s27, 0
	s_cselect_b32 s55, s26, 0
	s_ashr_i32 s19, s18, 31
	s_lshl_b64 s[24:25], s[18:19], 19
	s_add_u32 s19, s33, s24
	s_addc_u32 s21, s60, s25
	s_add_u32 s24, s19, s55
	s_addc_u32 s25, s21, s54
	s_and_b64 s[26:27], s[22:23], exec
	s_cselect_b32 s19, s25, s57
	s_cselect_b32 s31, s24, s56
	s_ashr_i32 s21, s20, 31
	s_lshl_b64 s[26:27], s[20:21], 19
	s_add_u32 s21, s2, s26
	s_addc_u32 s27, s3, s27
	s_add_u32 s26, s21, s55
	s_addc_u32 s27, s27, s54
	s_and_b64 s[54:55], s[22:23], exec
	s_cselect_b32 s21, s27, s35
	s_cselect_b32 s75, s26, s34
	s_cmp_gt_i32 s30, -1
	s_cselect_b64 s[54:55], -1, 0
	s_cmp_lt_i32 s30, 0
	s_cselect_b32 s76, 16, 4
	s_add_i32 s77, s76, -2
	s_add_u32 s56, s56, 0x40080
	s_addc_u32 s57, s57, 0
	s_add_u32 s78, s34, 0x100
	s_mov_b32 s58, 0
	s_addc_u32 s79, s35, 0
	ds_read_b128 v[18:21], v187
	ds_read_b128 v[26:29], v187 offset:2048
	ds_read_b128 v[22:25], v188
	ds_read_b128 v[30:33], v188 offset:2048
	ds_read_b128 v[2:5], v189
	ds_read_b128 v[10:13], v189 offset:2048
	ds_read_b128 v[6:9], v190
	ds_read_b128 v[14:17], v190 offset:2048
	s_add_i32 s80, s58, 2
	s_add_u32 s34, s56, 0xfffc0080
	s_addc_u32 s35, s57, -1
	s_cmp_eq_u32 s77, s58
	s_cselect_b32 s58, s31, s34
	s_cselect_b32 s59, s19, s35
	s_cselect_b32 s35, s21, s79
	s_cselect_b32 s34, s75, s78
	s_add_i32 m0, s29, 0xc000
	ds_read_b128 v[174:177], v191
	ds_read_b128 v[194:197], v191 offset:2048
	ds_read_b128 v[178:181], v192
	ds_read_b128 v[198:201], v192 offset:2048
	ds_read_b128 v[202:205], v191 offset:4096
	ds_read_b128 v[210:213], v191 offset:6144
	ds_read_b128 v[206:209], v192 offset:4096
	ds_read_b128 v[214:217], v192 offset:6144
	global_load_lds_dwordx4 v170, s[56:57]
	s_add_i32 m0, s29, 0xe000
	s_nop 0
	global_load_lds_dwordx4 v172, s[56:57]
	s_waitcnt vmcnt(8)
	s_waitcnt lgkmcnt(0)
	s_barrier
	s_setprio 1
	s_waitcnt lgkmcnt(0)
	v_mfma_scale_f32_16x16x128_f8f6f4 v[158:161], v[18:25], v[174:181], 0, v1, v182 op_sel_hi:[0,0,0]
	v_mfma_scale_f32_16x16x128_f8f6f4 v[154:157], v[26:33], v[174:181], 0, v1, v182 op_sel_hi:[0,0,0]
	v_mfma_scale_f32_16x16x128_f8f6f4 v[150:153], v[18:25], v[194:201], 0, v1, v182 op_sel_hi:[0,0,0]
	v_mfma_scale_f32_16x16x128_f8f6f4 v[138:141], v[26:33], v[194:201], 0, v1, v182 op_sel_hi:[0,0,0]
	v_mfma_scale_f32_16x16x128_f8f6f4 v[130:133], v[18:25], v[202:209], 0, v1, v182 op_sel_hi:[0,0,0]
	v_mfma_scale_f32_16x16x128_f8f6f4 v[122:125], v[26:33], v[202:209], 0, v1, v182 op_sel_hi:[0,0,0]
	v_mfma_scale_f32_16x16x128_f8f6f4 v[118:121], v[18:25], v[210:217], 0, v1, v182 op_sel_hi:[0,0,0]
	v_mfma_scale_f32_16x16x128_f8f6f4 v[106:109], v[26:33], v[210:217], 0, v1, v182 op_sel_hi:[0,0,0]
	s_setprio 0
	s_setprio 1
	v_mfma_scale_f32_16x16x128_f8f6f4 v[146:149], v[2:9], v[174:181], 0, v1, v182 op_sel_hi:[0,0,0]
	v_mfma_scale_f32_16x16x128_f8f6f4 v[142:145], v[10:17], v[174:181], 0, v1, v182 op_sel_hi:[0,0,0]
	v_mfma_scale_f32_16x16x128_f8f6f4 v[134:137], v[2:9], v[194:201], 0, v1, v182 op_sel_hi:[0,0,0]
	v_mfma_scale_f32_16x16x128_f8f6f4 v[126:129], v[10:17], v[194:201], 0, v1, v182 op_sel_hi:[0,0,0]
	v_mfma_scale_f32_16x16x128_f8f6f4 v[114:117], v[2:9], v[202:209], 0, v1, v182 op_sel_hi:[0,0,0]
	v_mfma_scale_f32_16x16x128_f8f6f4 v[110:113], v[10:17], v[202:209], 0, v1, v182 op_sel_hi:[0,0,0]
	v_mfma_scale_f32_16x16x128_f8f6f4 v[102:105], v[2:9], v[210:217], 0, v1, v182 op_sel_hi:[0,0,0]
	v_mfma_scale_f32_16x16x128_f8f6f4 v[98:101], v[10:17], v[210:217], 0, v1, v182 op_sel_hi:[0,0,0]
	s_setprio 0
	s_barrier
	s_add_i32 s81, s71, s61
	s_mov_b32 m0, s81
	ds_read_b128 v[194:197], v191 offset:16384
	ds_read_b128 v[202:205], v191 offset:18432
	ds_read_b128 v[198:201], v192 offset:16384
	ds_read_b128 v[206:209], v192 offset:18432
	ds_read_b128 v[210:213], v191 offset:20480
	ds_read_b128 v[218:221], v191 offset:22528
	ds_read_b128 v[214:217], v192 offset:20480
	ds_read_b128 v[222:225], v192 offset:22528
	global_load_lds_dwordx4 v164, s[34:35]
	s_add_i32 m0, s81, 0x2000
	s_add_u32 s82, s34, 0x40000
	s_addc_u32 s83, s35, 0
	s_add_i32 s81, s72, s61
	global_load_lds_dwordx4 v168, s[34:35]
	s_mov_b32 m0, s81
	s_nop 0
	global_load_lds_dwordx4 v164, s[82:83]
	s_add_i32 m0, s81, 0x2000
	s_nop 0
	global_load_lds_dwordx4 v168, s[82:83]
	s_mov_b32 m0, s29
	s_nop 0
	global_load_lds_dwordx4 v162, s[58:59]
	s_mov_b32 m0, s53
	s_nop 0
	global_load_lds_dwordx4 v166, s[58:59]
	s_waitcnt vmcnt(8)
	s_waitcnt lgkmcnt(0)
	s_barrier
	s_setprio 1
	s_waitcnt lgkmcnt(0)
	v_mfma_scale_f32_16x16x128_f8f6f4 v[94:97], v[18:25], v[194:201], 0, v1, v182 op_sel_hi:[0,0,0]
	v_mfma_scale_f32_16x16x128_f8f6f4 v[90:93], v[26:33], v[194:201], 0, v1, v182 op_sel_hi:[0,0,0]
	v_mfma_scale_f32_16x16x128_f8f6f4 v[82:85], v[18:25], v[202:209], 0, v1, v182 op_sel_hi:[0,0,0]
	v_mfma_scale_f32_16x16x128_f8f6f4 v[74:77], v[26:33], v[202:209], 0, v1, v182 op_sel_hi:[0,0,0]
	v_mfma_scale_f32_16x16x128_f8f6f4 v[66:69], v[18:25], v[210:217], 0, v1, v182 op_sel_hi:[0,0,0]
	v_mfma_scale_f32_16x16x128_f8f6f4 v[58:61], v[26:33], v[210:217], 0, v1, v182 op_sel_hi:[0,0,0]
	v_mfma_scale_f32_16x16x128_f8f6f4 v[50:53], v[18:25], v[218:225], 0, v1, v182 op_sel_hi:[0,0,0]
	v_mfma_scale_f32_16x16x128_f8f6f4 v[42:45], v[26:33], v[218:225], 0, v1, v182 op_sel_hi:[0,0,0]
	s_setprio 0
	s_setprio 1
	v_mfma_scale_f32_16x16x128_f8f6f4 v[86:89], v[2:9], v[194:201], 0, v1, v182 op_sel_hi:[0,0,0]
	v_mfma_scale_f32_16x16x128_f8f6f4 v[78:81], v[10:17], v[194:201], 0, v1, v182 op_sel_hi:[0,0,0]
	v_mfma_scale_f32_16x16x128_f8f6f4 v[70:73], v[2:9], v[202:209], 0, v1, v182 op_sel_hi:[0,0,0]
	v_mfma_scale_f32_16x16x128_f8f6f4 v[62:65], v[10:17], v[202:209], 0, v1, v182 op_sel_hi:[0,0,0]
	v_mfma_scale_f32_16x16x128_f8f6f4 v[54:57], v[2:9], v[210:217], 0, v1, v182 op_sel_hi:[0,0,0]
	v_mfma_scale_f32_16x16x128_f8f6f4 v[46:49], v[10:17], v[210:217], 0, v1, v182 op_sel_hi:[0,0,0]
	v_mfma_scale_f32_16x16x128_f8f6f4 v[38:41], v[2:9], v[218:225], 0, v1, v182 op_sel_hi:[0,0,0]
	v_mfma_scale_f32_16x16x128_f8f6f4 v[34:37], v[10:17], v[218:225], 0, v1, v182 op_sel_hi:[0,0,0]
	s_setprio 0
	s_barrier
	s_branch .Lmid_3
	.p2align	6

; #define PG8_STAGE(bufoff, gbase, voff) do { _Pragma("unroll") for (int _i = 0; _i < 2; ++_i) \
;         __builtin_amdgcn_global_load_lds((const unsigned*)((const char*)(gbase) + (voff)[_i]), (PG8_LAS unsigned*)(lds + (bufoff) + ldsw + _i * 8192), 16, 0, 0); } while (0)
; #define PG8_LDA(dst, b, h) do { _Pragma("unroll") for (int m = 0; m < 4; ++m) _Pragma("unroll") for (int k = 0; k < 2; ++k) dst[m][k] = *(const PG8_LAS bf16x8*)(lds + PG8_SA(b, h) + aoff + m * 2048 + k * 1024); } while (0)
; #define PG8_LDB(dst, b, h) do { _Pragma("unroll") for (int n = 0; n < 2; ++n) _Pragma("unroll") for (int k = 0; k < 2; ++k) dst[n][k] = *(const PG8_LAS bf16x8*)(lds + PG8_SB(b, h) + boff + n * 2048 + k * 1024); } while (0)
; #define PG8_WAIT_V(n) asm volatile("s_waitcnt vmcnt(" #n ")" ::: "memory")
; #define PG8_WAIT_L(n) asm volatile("s_waitcnt lgkmcnt(" #n ")" ::: "memory")
; #define PG8_BAR __builtin_amdgcn_s_barrier()
; #define PG8_SCHED __builtin_amdgcn_sched_barrier(0)
; #define PG8_BAR __builtin_amdgcn_s_barrier()
; template <class Epi, class Sched, bool ALIGN_EPI = false>
; __device__ __forceinline__ void gemm_phase8(PG8_LAS unsigned char* lds, const Gemm g, const Sched& S, const Epi& E) {
;     ...
;         const char* nA = has_next ? (const char*)g.A + (size_t)nxt.pm * tstepA + (size_t)nxt.pn * astep + nko : cA; const char* nB = has_next ? (const char*)g.Bt + (size_t)nxt.pn * tstepB + nko : cB;
;         const int nt = (cur.kp < 0 ? g.K : g.kpiece) / 128;
;         for (int t = 0; t < nt; t += 2) {
;             const bool last = (t == nt - 2);
;             const char* a1 = cA + (size_t)(t + 1) * kstep;
;             const char* a2 = last ? nA : cA + (size_t)(t + 2) * kstep; const char* b2 = last ? nB : cB + (size_t)(t + 2) * kstep;
;             const char* a3 = a2 + kstep; const char* b3 = b2 + kstep;
;             if (last && has_next) S.a_ready(nxt);
;             PG8_LDB(B0, 0, 0); PG8_LDB(B1, 0, 1); PG8_SCHED; PG8_LDA(At, 0, 0); PG8_STAGE(PG8_SA(1, 1), a1 + hstepA, voffA);
;             PG8_WAIT_V(8); PG8_WAIT_L(0); PG8_BAR; PG8_MMA(0, 0, At, B0); PG8_MMA(0, 1, At, B1); PG8_BAR; PG8_SCHED;
;             PG8_LDA(At, 0, 1); PG8_STAGE(PG8_SB(0, 0), b2, voffB); PG8_STAGE(PG8_SB(0, 1), b2 + hstepB, voffB); PG8_STAGE(PG8_SA(0, 0), a2, voffA);
;             PG8_WAIT_V(8); PG8_WAIT_L(0); PG8_BAR; PG8_MMA(1, 0, At, B0); PG8_MMA(1, 1, At, B1); PG8_BAR; PG8_SCHED;
.LBB0_1421:
	s_ashr_i32 s13, s12, 31
	s_lshl_b64 s[14:15], s[12:13], 19
	s_add_u32 s14, s26, s14
	s_addc_u32 s15, s27, s15
	s_and_b64 s[16:17], s[2:3], exec
	s_cselect_b32 s13, s15, s21
	s_cselect_b32 s45, s14, s20
	s_ashr_i32 s11, s10, 31
	s_lshl_b64 s[16:17], s[10:11], 19
	s_add_u32 s16, s28, s16
	s_addc_u32 s17, s29, s17
	s_and_b64 s[24:25], s[2:3], exec
	s_cselect_b32 s11, s17, s23
	s_cselect_b32 s52, s16, s22
	s_add_u32 s20, s20, 0x40080
	s_addc_u32 s21, s21, 0
	s_add_u32 s53, s22, 0x100
	s_addc_u32 s54, s23, 0
	s_mov_b32 s55, -2
	ds_read_b128 v[18:21], v191
	ds_read_b128 v[26:29], v191 offset:2048
	ds_read_b128 v[22:25], v192
	ds_read_b128 v[30:33], v192 offset:2048
	ds_read_b128 v[2:5], v193
	ds_read_b128 v[10:13], v193 offset:2048
	ds_read_b128 v[6:9], v194
	ds_read_b128 v[14:17], v194 offset:2048
	s_add_u32 s22, s20, 0xfffc0080
	s_addc_u32 s23, s21, -1
	s_cmp_eq_u32 s55, 12
	s_cselect_b32 s25, s13, s23
	s_cselect_b32 s24, s45, s22
	s_cselect_b32 s23, s11, s54
	s_cselect_b32 s22, s52, s53
	s_add_i32 m0, s19, 0xc000
	ds_read_b128 v[178:181], v195
	ds_read_b128 v[198:201], v195 offset:2048
	ds_read_b128 v[182:185], v196
	ds_read_b128 v[202:205], v196 offset:2048
	ds_read_b128 v[206:209], v195 offset:4096
	ds_read_b128 v[214:217], v195 offset:6144
	ds_read_b128 v[210:213], v196 offset:4096
	ds_read_b128 v[218:221], v196 offset:6144
	global_load_lds_dwordx4 v170, s[20:21]
	s_add_i32 m0, s19, 0xe000
	s_nop 0
	global_load_lds_dwordx4 v172, s[20:21]
	s_waitcnt vmcnt(8)
	s_waitcnt lgkmcnt(0)
	s_barrier
	s_setprio 1
	s_waitcnt lgkmcnt(0)
	v_mfma_scale_f32_16x16x128_f8f6f4 v[158:161], v[18:25], v[178:185], 0, v1, v186 op_sel_hi:[0,0,0]
	v_mfma_scale_f32_16x16x128_f8f6f4 v[150:153], v[26:33], v[178:185], 0, v1, v186 op_sel_hi:[0,0,0]
	v_mfma_scale_f32_16x16x128_f8f6f4 v[142:145], v[18:25], v[198:205], 0, v1, v186 op_sel_hi:[0,0,0]
	v_mfma_scale_f32_16x16x128_f8f6f4 v[134:137], v[26:33], v[198:205], 0, v1, v186 op_sel_hi:[0,0,0]
	v_mfma_scale_f32_16x16x128_f8f6f4 v[126:129], v[18:25], v[206:213], 0, v1, v186 op_sel_hi:[0,0,0]
	v_mfma_scale_f32_16x16x128_f8f6f4 v[118:121], v[26:33], v[206:213], 0, v1, v186 op_sel_hi:[0,0,0]
	v_mfma_scale_f32_16x16x128_f8f6f4 v[110:113], v[18:25], v[214:221], 0, v1, v186 op_sel_hi:[0,0,0]
	v_mfma_scale_f32_16x16x128_f8f6f4 v[102:105], v[26:33], v[214:221], 0, v1, v186 op_sel_hi:[0,0,0]
	s_setprio 0
	s_setprio 1
	v_mfma_scale_f32_16x16x128_f8f6f4 v[154:157], v[2:9], v[178:185], 0, v1, v186 op_sel_hi:[0,0,0]
	v_mfma_scale_f32_16x16x128_f8f6f4 v[146:149], v[10:17], v[178:185], 0, v1, v186 op_sel_hi:[0,0,0]
	v_mfma_scale_f32_16x16x128_f8f6f4 v[138:141], v[2:9], v[198:205], 0, v1, v186 op_sel_hi:[0,0,0]
	v_mfma_scale_f32_16x16x128_f8f6f4 v[130:133], v[10:17], v[198:205], 0, v1, v186 op_sel_hi:[0,0,0]
	v_mfma_scale_f32_16x16x128_f8f6f4 v[122:125], v[2:9], v[206:213], 0, v1, v186 op_sel_hi:[0,0,0]
	v_mfma_scale_f32_16x16x128_f8f6f4 v[114:117], v[10:17], v[206:213], 0, v1, v186 op_sel_hi:[0,0,0]
	v_mfma_scale_f32_16x16x128_f8f6f4 v[106:109], v[2:9], v[214:221], 0, v1, v186 op_sel_hi:[0,0,0]
	v_mfma_scale_f32_16x16x128_f8f6f4 v[98:101], v[10:17], v[214:221], 0, v1, v186 op_sel_hi:[0,0,0]
	s_setprio 0
	s_barrier
	s_add_i32 s56, s41, s30
	s_mov_b32 m0, s56
	ds_read_b128 v[198:201], v195 offset:16384
	ds_read_b128 v[206:209], v195 offset:18432
	ds_read_b128 v[202:205], v196 offset:16384
	ds_read_b128 v[210:213], v196 offset:18432
	ds_read_b128 v[214:217], v195 offset:20480
	ds_read_b128 v[222:225], v195 offset:22528
	ds_read_b128 v[218:221], v196 offset:20480
	ds_read_b128 v[226:229], v196 offset:22528
	global_load_lds_dwordx4 v164, s[22:23]
	s_add_i32 m0, s56, 0x2000
	s_add_u32 s56, s22, 0x40000
	s_addc_u32 s57, s23, 0
	s_add_i32 s58, s42, s30
	global_load_lds_dwordx4 v168, s[22:23]
	s_mov_b32 m0, s58
	s_nop 0
	global_load_lds_dwordx4 v164, s[56:57]
	s_add_i32 m0, s58, 0x2000
	s_nop 0
	global_load_lds_dwordx4 v168, s[56:57]
	s_mov_b32 m0, s19
	s_nop 0
	global_load_lds_dwordx4 v162, s[24:25]
	s_mov_b32 m0, s34
	s_nop 0
	global_load_lds_dwordx4 v166, s[24:25]
	s_waitcnt vmcnt(8)
	s_waitcnt lgkmcnt(0)
	s_barrier
	s_setprio 1
	s_waitcnt lgkmcnt(0)
	v_mfma_scale_f32_16x16x128_f8f6f4 v[94:97], v[18:25], v[198:205], 0, v1, v186 op_sel_hi:[0,0,0]
	v_mfma_scale_f32_16x16x128_f8f6f4 v[86:89], v[26:33], v[198:205], 0, v1, v186 op_sel_hi:[0,0,0]
	v_mfma_scale_f32_16x16x128_f8f6f4 v[78:81], v[18:25], v[206:213], 0, v1, v186 op_sel_hi:[0,0,0]
	v_mfma_scale_f32_16x16x128_f8f6f4 v[70:73], v[26:33], v[206:213], 0, v1, v186 op_sel_hi:[0,0,0]
	v_mfma_scale_f32_16x16x128_f8f6f4 v[62:65], v[18:25], v[214:221], 0, v1, v186 op_sel_hi:[0,0,0]
	v_mfma_scale_f32_16x16x128_f8f6f4 v[54:57], v[26:33], v[214:221], 0, v1, v186 op_sel_hi:[0,0,0]
	v_mfma_scale_f32_16x16x128_f8f6f4 v[46:49], v[18:25], v[222:229], 0, v1, v186 op_sel_hi:[0,0,0]
	v_mfma_scale_f32_16x16x128_f8f6f4 v[38:41], v[26:33], v[222:229], 0, v1, v186 op_sel_hi:[0,0,0]
	s_setprio 0
	s_setprio 1
	v_mfma_scale_f32_16x16x128_f8f6f4 v[90:93], v[2:9], v[198:205], 0, v1, v186 op_sel_hi:[0,0,0]
	v_mfma_scale_f32_16x16x128_f8f6f4 v[82:85], v[10:17], v[198:205], 0, v1, v186 op_sel_hi:[0,0,0]
	v_mfma_scale_f32_16x16x128_f8f6f4 v[74:77], v[2:9], v[206:213], 0, v1, v186 op_sel_hi:[0,0,0]
	v_mfma_scale_f32_16x16x128_f8f6f4 v[66:69], v[10:17], v[206:213], 0, v1, v186 op_sel_hi:[0,0,0]
	v_mfma_scale_f32_16x16x128_f8f6f4 v[58:61], v[2:9], v[214:221], 0, v1, v186 op_sel_hi:[0,0,0]
	v_mfma_scale_f32_16x16x128_f8f6f4 v[50:53], v[10:17], v[214:221], 0, v1, v186 op_sel_hi:[0,0,0]
	v_mfma_scale_f32_16x16x128_f8f6f4 v[42:45], v[2:9], v[222:229], 0, v1, v186 op_sel_hi:[0,0,0]
	v_mfma_scale_f32_16x16x128_f8f6f4 v[34:37], v[10:17], v[222:229], 0, v1, v186 op_sel_hi:[0,0,0]
	s_setprio 0
	s_barrier
	s_branch .Lmid_4
	.p2align	6

; #define PG8_STAGE(bufoff, gbase, voff) do { _Pragma("unroll") for (int _i = 0; _i < 2; ++_i) \
;         __builtin_amdgcn_global_load_lds((const unsigned*)((const char*)(gbase) + (voff)[_i]), (PG8_LAS unsigned*)(lds + (bufoff) + ldsw + _i * 8192), 16, 0, 0); } while (0)
; #define PG8_LDA(dst, b, h) do { _Pragma("unroll") for (int m = 0; m < 4; ++m) _Pragma("unroll") for (int k = 0; k < 2; ++k) dst[m][k] = *(const PG8_LAS bf16x8*)(lds + PG8_SA(b, h) + aoff + m * 2048 + k * 1024); } while (0)
; #define PG8_LDB(dst, b, h) do { _Pragma("unroll") for (int n = 0; n < 2; ++n) _Pragma("unroll") for (int k = 0; k < 2; ++k) dst[n][k] = *(const PG8_LAS bf16x8*)(lds + PG8_SB(b, h) + boff + n * 2048 + k * 1024); } while (0)
; #define PG8_MMA(ai, bj, At, Bt) do { __builtin_amdgcn_s_setprio(1); _Pragma("unroll") for (int m = 0; m < 4; ++m) _Pragma("unroll") for (int n = 0; n < 2; ++n) _Pragma("unroll") for (int k = 0; k < 2; ++k) \
;         acc[ai][bj][m][n] = __builtin_amdgcn_mfma_f32_16x16x32_bf16(Bt[n][k], At[m][k], acc[ai][bj][m][n], 0, 0, 0); __builtin_amdgcn_s_setprio(0); } while (0)
; #define PG8_WAIT_V(n) asm volatile("s_waitcnt vmcnt(" #n ")" ::: "memory")
; #define PG8_BAR __builtin_amdgcn_s_barrier()
; template <class Epi, class Sched, bool ALIGN_EPI = false>
; __device__ __forceinline__ void gemm_phase8(PG8_LAS unsigned char* lds, const Gemm g, const Sched& S, const Epi& E) {
;     ...
;         const int nt = (cur.kp < 0 ? g.K : g.kpiece) / 128;
;         for (int t = 0; t < nt; t += 2) {
;             const bool last = (t == nt - 2);
;             const char* a1 = cA + (size_t)(t + 1) * kstep;
;             const char* a2 = last ? nA : cA + (size_t)(t + 2) * kstep; const char* b2 = last ? nB : cB + (size_t)(t + 2) * kstep;
;             const char* a3 = a2 + kstep; const char* b3 = b2 + kstep;
;             if (last && has_next) S.a_ready(nxt);
;             PG8_LDB(B0, 0, 0); PG8_LDB(B1, 0, 1); PG8_SCHED; PG8_LDA(At, 0, 0); PG8_STAGE(PG8_SA(1, 1), a1 + hstepA, voffA);
;             PG8_WAIT_V(8); PG8_WAIT_L(0); PG8_BAR; PG8_MMA(0, 0, At, B0); PG8_MMA(0, 1, At, B1); PG8_BAR; PG8_SCHED;
;             PG8_LDA(At, 0, 1); PG8_STAGE(PG8_SB(0, 0), b2, voffB); PG8_STAGE(PG8_SB(0, 1), b2 + hstepB, voffB); PG8_STAGE(PG8_SA(0, 0), a2, voffA);
;             PG8_WAIT_V(8); PG8_WAIT_L(0); PG8_BAR; PG8_MMA(1, 0, At, B0); PG8_MMA(1, 1, At, B1); PG8_BAR; PG8_SCHED;
.LBB0_1510:
	s_cmp_gt_i32 s30, -1
	s_cselect_b64 s[36:37], -1, 0
	s_cmp_lt_i32 s30, 0
	s_cselect_b32 s31, 44, 4
	s_add_i32 s79, s31, -2
	s_add_u32 s38, s38, 0xb0080
	s_addc_u32 s39, s39, 0
	s_add_u32 s80, s34, 0x100
	s_mov_b32 s40, 0
	s_addc_u32 s81, s35, 0
	ds_read_b128 v[18:21], v187
	ds_read_b128 v[26:29], v187 offset:2048
	ds_read_b128 v[22:25], v188
	ds_read_b128 v[30:33], v188 offset:2048
	ds_read_b128 v[2:5], v189
	ds_read_b128 v[10:13], v189 offset:2048
	ds_read_b128 v[6:9], v190
	ds_read_b128 v[14:17], v190 offset:2048
	s_add_i32 s82, s40, 2
	s_add_u32 s34, s38, 0xfff50080
	s_addc_u32 s35, s39, -1
	s_cmp_eq_u32 s79, s40
	s_cselect_b32 s40, s26, s34
	s_cselect_b32 s41, s27, s35
	s_cselect_b32 s35, s29, s81
	s_cselect_b32 s34, s28, s80
	s_add_i32 m0, s52, 0xc000
	ds_read_b128 v[174:177], v191
	ds_read_b128 v[194:197], v191 offset:2048
	ds_read_b128 v[178:181], v192
	ds_read_b128 v[198:201], v192 offset:2048
	ds_read_b128 v[202:205], v191 offset:4096
	ds_read_b128 v[210:213], v191 offset:6144
	ds_read_b128 v[206:209], v192 offset:4096
	ds_read_b128 v[214:217], v192 offset:6144
	global_load_lds_dwordx4 v170, s[38:39]
	s_add_i32 m0, s52, 0xe000
	s_nop 0
	global_load_lds_dwordx4 v172, s[38:39]
	s_waitcnt vmcnt(8)
	s_waitcnt lgkmcnt(0)
	s_barrier
	s_setprio 1
	s_waitcnt lgkmcnt(0)
	v_mfma_scale_f32_16x16x128_f8f6f4 v[158:161], v[18:25], v[174:181], 0, v1, v182 op_sel_hi:[0,0,0]
	v_mfma_scale_f32_16x16x128_f8f6f4 v[154:157], v[26:33], v[174:181], 0, v1, v182 op_sel_hi:[0,0,0]
	v_mfma_scale_f32_16x16x128_f8f6f4 v[150:153], v[18:25], v[194:201], 0, v1, v182 op_sel_hi:[0,0,0]
	v_mfma_scale_f32_16x16x128_f8f6f4 v[138:141], v[26:33], v[194:201], 0, v1, v182 op_sel_hi:[0,0,0]
	v_mfma_scale_f32_16x16x128_f8f6f4 v[130:133], v[18:25], v[202:209], 0, v1, v182 op_sel_hi:[0,0,0]
	v_mfma_scale_f32_16x16x128_f8f6f4 v[122:125], v[26:33], v[202:209], 0, v1, v182 op_sel_hi:[0,0,0]
	v_mfma_scale_f32_16x16x128_f8f6f4 v[118:121], v[18:25], v[210:217], 0, v1, v182 op_sel_hi:[0,0,0]
	v_mfma_scale_f32_16x16x128_f8f6f4 v[106:109], v[26:33], v[210:217], 0, v1, v182 op_sel_hi:[0,0,0]
	s_setprio 0
	s_setprio 1
	v_mfma_scale_f32_16x16x128_f8f6f4 v[146:149], v[2:9], v[174:181], 0, v1, v182 op_sel_hi:[0,0,0]
	v_mfma_scale_f32_16x16x128_f8f6f4 v[142:145], v[10:17], v[174:181], 0, v1, v182 op_sel_hi:[0,0,0]
	v_mfma_scale_f32_16x16x128_f8f6f4 v[134:137], v[2:9], v[194:201], 0, v1, v182 op_sel_hi:[0,0,0]
	v_mfma_scale_f32_16x16x128_f8f6f4 v[126:129], v[10:17], v[194:201], 0, v1, v182 op_sel_hi:[0,0,0]
	v_mfma_scale_f32_16x16x128_f8f6f4 v[114:117], v[2:9], v[202:209], 0, v1, v182 op_sel_hi:[0,0,0]
	v_mfma_scale_f32_16x16x128_f8f6f4 v[110:113], v[10:17], v[202:209], 0, v1, v182 op_sel_hi:[0,0,0]
	v_mfma_scale_f32_16x16x128_f8f6f4 v[102:105], v[2:9], v[210:217], 0, v1, v182 op_sel_hi:[0,0,0]
	v_mfma_scale_f32_16x16x128_f8f6f4 v[98:101], v[10:17], v[210:217], 0, v1, v182 op_sel_hi:[0,0,0]
	s_setprio 0
	s_barrier
	s_add_i32 s83, s63, s45
	s_mov_b32 m0, s83
	ds_read_b128 v[194:197], v191 offset:16384
	ds_read_b128 v[202:205], v191 offset:18432
	ds_read_b128 v[198:201], v192 offset:16384
	ds_read_b128 v[206:209], v192 offset:18432
	ds_read_b128 v[210:213], v191 offset:20480
	ds_read_b128 v[218:221], v191 offset:22528
	ds_read_b128 v[214:217], v192 offset:20480
	ds_read_b128 v[222:225], v192 offset:22528
	global_load_lds_dwordx4 v164, s[34:35]
	s_add_i32 m0, s83, 0x2000
	s_add_u32 s84, s34, 0xb0000
	s_addc_u32 s85, s35, 0
	s_add_i32 s83, s64, s45
	global_load_lds_dwordx4 v168, s[34:35]
	s_mov_b32 m0, s83
	s_nop 0
	global_load_lds_dwordx4 v164, s[84:85]
	s_add_i32 m0, s83, 0x2000
	s_nop 0
	global_load_lds_dwordx4 v168, s[84:85]
	s_mov_b32 m0, s52
	s_nop 0
	global_load_lds_dwordx4 v162, s[40:41]
	s_mov_b32 m0, s53
	s_nop 0
	global_load_lds_dwordx4 v166, s[40:41]
	s_waitcnt vmcnt(8)
	s_waitcnt lgkmcnt(0)
	s_barrier
	s_setprio 1
	s_waitcnt lgkmcnt(0)
	v_mfma_scale_f32_16x16x128_f8f6f4 v[94:97], v[18:25], v[194:201], 0, v1, v182 op_sel_hi:[0,0,0]
	v_mfma_scale_f32_16x16x128_f8f6f4 v[90:93], v[26:33], v[194:201], 0, v1, v182 op_sel_hi:[0,0,0]
	v_mfma_scale_f32_16x16x128_f8f6f4 v[82:85], v[18:25], v[202:209], 0, v1, v182 op_sel_hi:[0,0,0]
	v_mfma_scale_f32_16x16x128_f8f6f4 v[74:77], v[26:33], v[202:209], 0, v1, v182 op_sel_hi:[0,0,0]
	v_mfma_scale_f32_16x16x128_f8f6f4 v[66:69], v[18:25], v[210:217], 0, v1, v182 op_sel_hi:[0,0,0]
	v_mfma_scale_f32_16x16x128_f8f6f4 v[58:61], v[26:33], v[210:217], 0, v1, v182 op_sel_hi:[0,0,0]
	v_mfma_scale_f32_16x16x128_f8f6f4 v[50:53], v[18:25], v[218:225], 0, v1, v182 op_sel_hi:[0,0,0]
	v_mfma_scale_f32_16x16x128_f8f6f4 v[42:45], v[26:33], v[218:225], 0, v1, v182 op_sel_hi:[0,0,0]
	s_setprio 0
	s_setprio 1
	v_mfma_scale_f32_16x16x128_f8f6f4 v[86:89], v[2:9], v[194:201], 0, v1, v182 op_sel_hi:[0,0,0]
	v_mfma_scale_f32_16x16x128_f8f6f4 v[78:81], v[10:17], v[194:201], 0, v1, v182 op_sel_hi:[0,0,0]
	v_mfma_scale_f32_16x16x128_f8f6f4 v[70:73], v[2:9], v[202:209], 0, v1, v182 op_sel_hi:[0,0,0]
	v_mfma_scale_f32_16x16x128_f8f6f4 v[62:65], v[10:17], v[202:209], 0, v1, v182 op_sel_hi:[0,0,0]
	v_mfma_scale_f32_16x16x128_f8f6f4 v[54:57], v[2:9], v[210:217], 0, v1, v182 op_sel_hi:[0,0,0]
	v_mfma_scale_f32_16x16x128_f8f6f4 v[46:49], v[10:17], v[210:217], 0, v1, v182 op_sel_hi:[0,0,0]
	v_mfma_scale_f32_16x16x128_f8f6f4 v[38:41], v[2:9], v[218:225], 0, v1, v182 op_sel_hi:[0,0,0]
	v_mfma_scale_f32_16x16x128_f8f6f4 v[34:37], v[10:17], v[218:225], 0, v1, v182 op_sel_hi:[0,0,0]
	s_setprio 0
	s_barrier
	s_branch .Lmid_5
	.p2align	6
